# z1 + attention lazy-rescale branch tests on s[6:7] directly (v_cmp removed) with the rare rescale blocks moved out of line (GQA and MLA loops); rare path exercised with a threshold-0 test build
# speedup vs baseline: 1.0138x; 1.0064x over previous
.Lgqa_joinA:
	s_barrier
	v_cndmask_b32_e64 v217, v251, 1.0, s[6:7]
	ds_write_b128 v195, v[128:131]
	ds_write_b128 v196, v[132:135]
	s_and_b64 vcc, exec, s[6:7]
	s_cbranch_vccz .Lresc_743
.LBB0_743:
	v_cndmask_b32_e64 v216, v250, v174, s[6:7]
	v_mul_f32_e32 v212, 0xbe0293ee, v216
	v_fmamk_f32 v162, v80, 0x3e0293ee, v212
	v_fmamk_f32 v177, v81, 0x3e0293ee, v212
	v_fmamk_f32 v163, v82, 0x3e0293ee, v212
	v_fmamk_f32 v176, v83, 0x3e0293ee, v212
	v_fmamk_f32 v164, v84, 0x3e0293ee, v212
	v_fmamk_f32 v175, v85, 0x3e0293ee, v212
	v_fmamk_f32 v165, v86, 0x3e0293ee, v212
	v_fmamk_f32 v174, v87, 0x3e0293ee, v212
	v_fmamk_f32 v166, v88, 0x3e0293ee, v212
	v_fmamk_f32 v173, v89, 0x3e0293ee, v212
	v_fmamk_f32 v167, v90, 0x3e0293ee, v212
	v_fmamk_f32 v172, v91, 0x3e0293ee, v212
	v_fmamk_f32 v168, v92, 0x3e0293ee, v212
	v_fmamk_f32 v171, v93, 0x3e0293ee, v212
	v_fmamk_f32 v169, v94, 0x3e0293ee, v212
	v_fmamk_f32 v170, v95, 0x3e0293ee, v212
	ds_read_b128 v[240:243], v200 offset:32768
	ds_read_b128 v[244:247], v208 offset:32768
	ds_read_b128 v[248:251], v207 offset:32768
	s_waitcnt lgkmcnt(2)
	v_mfma_f32_32x32x16_bf16 v[80:95], v[240:243], v[124:127], 0
	ds_read_b128 v[240:243], v206 offset:32768
	v_exp_f32_e32 v162, v162
	v_exp_f32_e32 v177, v177
	v_fmamk_f32 v219, v70, 0x3e0293ee, v212
	s_waitcnt lgkmcnt(2)
	v_mfma_f32_32x32x16_bf16 v[80:95], v[244:247], v[120:123], v[80:95]
	ds_read_b128 v[244:247], v205 offset:32768
	v_exp_f32_e32 v163, v163
	v_exp_f32_e32 v176, v176
	v_fmamk_f32 v220, v71, 0x3e0293ee, v212
	s_waitcnt lgkmcnt(2)
	v_mfma_f32_32x32x16_bf16 v[80:95], v[248:251], v[116:119], v[80:95]
	ds_read_b128 v[248:251], v204 offset:32768
	v_exp_f32_e32 v164, v164
	v_exp_f32_e32 v175, v175
	v_fmamk_f32 v225, v64, 0x3e0293ee, v212
	s_waitcnt lgkmcnt(2)
	v_mfma_f32_32x32x16_bf16 v[80:95], v[240:243], v[112:115], v[80:95]
	ds_read_b128 v[240:243], v202 offset:32768
	v_exp_f32_e32 v165, v165
	v_exp_f32_e32 v174, v174
	v_fmamk_f32 v226, v65, 0x3e0293ee, v212
	s_waitcnt lgkmcnt(2)
	v_mfma_f32_32x32x16_bf16 v[80:95], v[244:247], v[108:111], v[80:95]
	ds_read_b128 v[244:247], v201 offset:32768
	v_exp_f32_e32 v166, v166
	v_exp_f32_e32 v173, v173
	v_fmamk_f32 v227, v66, 0x3e0293ee, v212
	s_waitcnt lgkmcnt(2)
	v_mfma_f32_32x32x16_bf16 v[80:95], v[248:251], v[104:107], v[80:95]
	ds_read_b128 v[248:251], v200 offset:40960
	v_exp_f32_e32 v167, v167
	v_exp_f32_e32 v172, v172
	v_fmamk_f32 v232, v67, 0x3e0293ee, v212
	s_waitcnt lgkmcnt(2)
	v_mfma_f32_32x32x16_bf16 v[80:95], v[240:243], v[100:103], v[80:95]
	ds_read_b128 v[240:243], v208 offset:40960
	v_exp_f32_e32 v168, v168
	v_exp_f32_e32 v171, v171
	v_fmamk_f32 v233, v68, 0x3e0293ee, v212
	s_waitcnt lgkmcnt(2)
	v_mfma_f32_32x32x16_bf16 v[80:95], v[244:247], v[96:99], v[80:95]
	ds_read_b128 v[244:247], v207 offset:40960
	v_exp_f32_e32 v169, v169
	v_exp_f32_e32 v170, v170
	v_fmamk_f32 v218, v69, 0x3e0293ee, v212
	v_fmamk_f32 v221, v72, 0x3e0293ee, v212
	v_fmamk_f32 v222, v73, 0x3e0293ee, v212
	v_fmamk_f32 v223, v74, 0x3e0293ee, v212
	v_fmamk_f32 v224, v75, 0x3e0293ee, v212
	v_fmamk_f32 v213, v76, 0x3e0293ee, v212
	v_fmamk_f32 v234, v77, 0x3e0293ee, v212
	v_fmamk_f32 v235, v78, 0x3e0293ee, v212
	v_fmac_f32_e32 v212, 0x3e0293ee, v79
	s_waitcnt lgkmcnt(2)
	v_mfma_f32_32x32x16_bf16 v[64:79], v[248:251], v[124:127], 0
	ds_read_b128 v[248:251], v206 offset:40960
	v_exp_f32_e32 v215, v226
	v_exp_f32_e32 v226, v232
	s_waitcnt lgkmcnt(2)
	v_mfma_f32_32x32x16_bf16 v[64:79], v[240:243], v[120:123], v[64:79]
	ds_read_b128 v[240:243], v205 offset:40960
	v_exp_f32_e32 v232, v219
	v_add_f32_e32 v219, 0, v162
	v_add_f32_e32 v219, v177, v219
	v_add_f32_e32 v219, v163, v219
	s_waitcnt lgkmcnt(2)
	v_mfma_f32_32x32x16_bf16 v[64:79], v[244:247], v[116:119], v[64:79]
	ds_read_b128 v[244:247], v204 offset:40960
	v_add_f32_e32 v219, v176, v219
	v_add_f32_e32 v219, v164, v219
	v_add_f32_e32 v219, v175, v219
	v_add_f32_e32 v219, v165, v219
	v_add_f32_e32 v219, v174, v219
	s_waitcnt lgkmcnt(2)
	v_mfma_f32_32x32x16_bf16 v[64:79], v[248:251], v[112:115], v[64:79]
	ds_read_b128 v[248:251], v202 offset:40960
	v_add_f32_e32 v219, v166, v219
	v_add_f32_e32 v219, v173, v219
	v_add_f32_e32 v219, v167, v219
	v_add_f32_e32 v219, v172, v219
	v_add_f32_e32 v219, v168, v219
	s_waitcnt lgkmcnt(2)
	v_mfma_f32_32x32x16_bf16 v[64:79], v[240:243], v[108:111], v[64:79]
	ds_read_b128 v[240:243], v201 offset:40960
	v_exp_f32_e32 v214, v225
	v_add_f32_e32 v219, v171, v219
	v_exp_f32_e32 v225, v227
	s_waitcnt lgkmcnt(2)
	v_mfma_f32_32x32x16_bf16 v[64:79], v[244:247], v[104:107], v[64:79]
	v_add_f32_e32 v219, v169, v219
	v_add_f32_e32 v219, v170, v219
	v_exp_f32_e32 v227, v233
	v_add_f32_e32 v219, v214, v219
	s_waitcnt lgkmcnt(1)
	v_mfma_f32_32x32x16_bf16 v[64:79], v[248:251], v[100:103], v[64:79]
	v_exp_f32_e32 v218, v218
	v_add_f32_e32 v219, v215, v219
	v_add_f32_e32 v219, v225, v219
	v_add_f32_e32 v219, v226, v219
	s_waitcnt lgkmcnt(0)
	v_mfma_f32_32x32x16_bf16 v[64:79], v[240:243], v[96:99], v[64:79]
	v_exp_f32_e32 v233, v220
	v_exp_f32_e32 v221, v221
	v_add_f32_e32 v219, v227, v219
	s_cmp_ge_u32 s14, s91
	s_cselect_b64 s[10:11], -1, 0
	s_waitcnt vmcnt(0)
	ds_write_b128 v198, v[154:157] offset:49152
	ds_write_b128 v199, v[158:161] offset:49152
	s_ashr_i32 s9, s8, 31
	s_mul_hi_u32 s100, s8, s40
	s_mul_i32 s101, s8, s41
	s_add_u32 s100, s100, s101
	s_mul_i32 s101, s9, s40
	s_add_u32 s100, s100, s101
	s_mul_i32 s6, s8, s40
	s_mov_b32 s7, s100
	s_lshl_b64 s[6:7], s[6:7], 1
	v_exp_f32_e32 v222, v222
	v_add_f32_e32 v219, v218, v219
	v_exp_f32_e32 v223, v223
	v_add_f32_e32 v219, v232, v219
	v_exp_f32_e32 v224, v224
	v_add_f32_e32 v219, v233, v219
	v_exp_f32_e32 v213, v213
	v_add_f32_e32 v219, v221, v219
	v_exp_f32_e32 v234, v234
	v_add_f32_e32 v219, v222, v219
	v_exp_f32_e32 v235, v235
	v_add_f32_e32 v219, v223, v219
	v_exp_f32_e32 v212, v212
	v_add_f32_e32 v219, v224, v219
	v_add_f32_e32 v219, v213, v219
	v_add_f32_e32 v219, v234, v219
	v_add_f32_e32 v219, v235, v219
	v_add_f32_e32 v219, v212, v219
	v_cvt_pk_bf16_f32 v162, v162, v177
	v_cvt_pk_bf16_f32 v163, v163, v176
	v_cvt_pk_bf16_f32 v164, v164, v175
	v_cvt_pk_bf16_f32 v165, v165, v174
	v_cvt_pk_bf16_f32 v169, v169, v170
	v_cvt_pk_bf16_f32 v170, v214, v215
	v_cvt_pk_bf16_f32 v176, v213, v234
	v_cvt_pk_bf16_f32 v177, v235, v212
	v_permlane32_swap_b32_e32 v162, v164
	v_permlane32_swap_b32_e32 v163, v165
	ds_read_b64_tr_b16 v[212:213], v197 offset:0
	ds_read_b64_tr_b16 v[214:215], v197 offset:0x800
	s_waitcnt lgkmcnt(0)
	v_mfma_f32_32x32x16_bf16 v[48:63], v[162:165], v[212:215], v[48:63]
	v_mov_b32_e32 v220, v219
	s_nop 1
	v_permlane32_swap_b32_e32 v219, v220
	v_cvt_pk_bf16_f32 v166, v166, v173
	v_cvt_pk_bf16_f32 v167, v167, v172
	v_cvt_pk_bf16_f32 v168, v168, v171
	v_cvt_pk_bf16_f32 v171, v225, v226
	v_cvt_pk_bf16_f32 v174, v221, v222
	v_cvt_pk_bf16_f32 v175, v223, v224
	v_permlane32_swap_b32_e32 v166, v168
	v_permlane32_swap_b32_e32 v167, v169
	ds_read_b64_tr_b16 v[222:223], v197 offset:0x1000
	ds_read_b64_tr_b16 v[224:225], v197 offset:0x1800
	s_waitcnt lgkmcnt(0)
	v_mfma_f32_32x32x16_bf16 v[48:63], v[166:169], v[222:225], v[48:63]
	v_cvt_pk_bf16_f32 v172, v227, v218
	v_cvt_pk_bf16_f32 v173, v232, v233
	s_nop 0
	v_permlane32_swap_b32_e32 v170, v172
	v_permlane32_swap_b32_e32 v171, v173
	v_permlane32_swap_b32_e32 v174, v176
	ds_read_b64_tr_b16 v[232:233], v197 offset:0x2000
	ds_read_b64_tr_b16 v[234:235], v197 offset:0x2800
	ds_read_b64_tr_b16 v[236:237], v197 offset:0x3000
	ds_read_b64_tr_b16 v[238:239], v197 offset:0x3800
	ds_read_b64_tr_b16 v[212:213], v197 offset:0x200
	ds_read_b64_tr_b16 v[214:215], v197 offset:0xa00
	ds_read_b64_tr_b16 v[222:223], v197 offset:0x1200
	ds_read_b64_tr_b16 v[224:225], v197 offset:0x1a00
	s_waitcnt lgkmcnt(6)
	v_mfma_f32_32x32x16_bf16 v[48:63], v[170:173], v[232:235], v[48:63]
	ds_read_b64_tr_b16 v[232:233], v197 offset:0x2200
	ds_read_b64_tr_b16 v[234:235], v197 offset:0x2a00
	v_permlane32_swap_b32_e32 v175, v177
	v_lshl_add_u64 v[128:129], s[6:7], 0, v[178:179]
	v_lshl_add_u64 v[132:133], s[6:7], 0, v[180:181]
	v_lshl_add_u64 v[136:137], s[6:7], 0, v[182:183]
	v_lshl_add_u64 v[140:141], s[6:7], 0, v[184:185]
	s_waitcnt lgkmcnt(6)
	v_mfma_f32_32x32x16_bf16 v[48:63], v[174:177], v[236:239], v[48:63]
	ds_read_b64_tr_b16 v[236:237], v197 offset:0x3200
	ds_read_b64_tr_b16 v[238:239], v197 offset:0x3a00
	v_max_f32_e32 v250, v81, v81
	v_max_f32_e32 v251, v80, v80
	v_max_f32_e32 v250, v251, v250
	v_max3_f32 v250, v250, v82, v83
	v_max3_f32 v250, v250, v84, v85
	s_waitcnt lgkmcnt(6)
	v_mfma_f32_32x32x16_bf16 v[32:47], v[162:165], v[212:215], v[32:47]
	ds_read_b64_tr_b16 v[212:213], v197 offset:0x400
	ds_read_b64_tr_b16 v[214:215], v197 offset:0xc00
	v_max3_f32 v250, v250, v86, v87
	v_max3_f32 v250, v250, v88, v89
	v_max3_f32 v250, v250, v90, v91
	v_max3_f32 v250, v250, v92, v93
	v_max3_f32 v250, v250, v94, v95
	s_waitcnt lgkmcnt(6)
	v_mfma_f32_32x32x16_bf16 v[32:47], v[166:169], v[222:225], v[32:47]
	ds_read_b64_tr_b16 v[222:223], v197 offset:0x1400
	ds_read_b64_tr_b16 v[224:225], v197 offset:0x1c00
	v_max3_f32 v250, v250, v64, v65
	v_max3_f32 v250, v250, v66, v67
	v_max3_f32 v250, v250, v68, v69
	v_max3_f32 v250, v250, v70, v71
	v_max3_f32 v250, v250, v72, v73
	global_load_dwordx4 v[128:131], v[128:129], off
	global_load_dwordx4 v[132:135], v[132:133], off
	global_load_dwordx4 v[136:139], v[136:137], off
	global_load_dwordx4 v[140:143], v[140:141], off
	s_waitcnt lgkmcnt(6)
	v_mfma_f32_32x32x16_bf16 v[32:47], v[170:173], v[232:235], v[32:47]
	ds_read_b64_tr_b16 v[232:233], v197 offset:0x2400
	ds_read_b64_tr_b16 v[234:235], v197 offset:0x2c00
	v_max3_f32 v250, v250, v74, v75
	v_max3_f32 v250, v250, v76, v77
	v_max3_f32 v250, v250, v78, v79
	v_mov_b32_e32 v251, v250
	s_nop 1
	v_permlane32_swap_b32_e32 v250, v251
	s_waitcnt lgkmcnt(6)
	v_mfma_f32_32x32x16_bf16 v[32:47], v[174:177], v[236:239], v[32:47]
	ds_read_b64_tr_b16 v[236:237], v197 offset:0x3400
	ds_read_b64_tr_b16 v[238:239], v197 offset:0x3c00
	v_max_f32_e32 v251, v251, v251
	v_max_f32_e32 v250, v250, v250
	v_max_f32_e32 v250, v250, v251
	v_sub_f32_e32 v251, v250, v216
	v_cmp_ge_f32_e32 vcc, s93, v251
	s_waitcnt lgkmcnt(6)
	v_mfma_f32_32x32x16_bf16 v[16:31], v[162:165], v[212:215], v[16:31]
	ds_read_b64_tr_b16 v[212:213], v197 offset:0x600
	ds_read_b64_tr_b16 v[214:215], v197 offset:0xe00
	v_max_f32_e32 v251, v216, v216
	v_max_f32_e32 v250, v251, v250
	v_sub_f32_e32 v251, v216, v250
	v_mul_f32_e32 v251, 0x3e0293ee, v251
	s_waitcnt lgkmcnt(6)
	v_mfma_f32_32x32x16_bf16 v[16:31], v[166:169], v[222:225], v[16:31]
	ds_read_b64_tr_b16 v[222:223], v197 offset:0x1600
	ds_read_b64_tr_b16 v[224:225], v197 offset:0x1e00
	v_exp_f32_e32 v251, v251
	s_waitcnt lgkmcnt(6)
	v_mfma_f32_32x32x16_bf16 v[16:31], v[170:173], v[232:235], v[16:31]
	ds_read_b64_tr_b16 v[232:233], v197 offset:0x2600
	ds_read_b64_tr_b16 v[234:235], v197 offset:0x2e00
	s_waitcnt lgkmcnt(6)
	v_mfma_f32_32x32x16_bf16 v[16:31], v[174:177], v[236:239], v[16:31]
	ds_read_b64_tr_b16 v[236:237], v197 offset:0x3600
	ds_read_b64_tr_b16 v[238:239], v197 offset:0x3e00
	s_waitcnt lgkmcnt(6)
	v_mfma_f32_32x32x16_bf16 v[0:15], v[162:165], v[212:215], v[0:15]
	s_waitcnt lgkmcnt(4)
	v_mfma_f32_32x32x16_bf16 v[0:15], v[166:169], v[222:225], v[0:15]
	s_waitcnt lgkmcnt(2)
	v_mfma_f32_32x32x16_bf16 v[0:15], v[170:173], v[232:235], v[0:15]
	s_waitcnt lgkmcnt(0)
	v_mfma_f32_32x32x16_bf16 v[0:15], v[174:177], v[236:239], v[0:15]
	s_cmp_eq_u64 vcc, exec
	s_cselect_b64 s[6:7], -1, 0
	s_barrier
	v_cndmask_b32_e64 v218, v251, 1.0, s[6:7]
	ds_write_b128 v195, v[146:149] offset:16384
	ds_write_b128 v196, v[150:153] offset:16384
	s_and_b64 vcc, exec, s[6:7]
	s_cbranch_vccz .Lresc_749

.Lresc_749:
	s_and_saveexec_b64 s[12:13], s[4:5]
	ds_write_b32 v194, v218 offset:128
	s_or_b64 exec, exec, s[12:13]
	s_waitcnt lgkmcnt(0)
	v_add_u32_e32 v158, v192, v144
	ds_read_b128 v[146:149], v158 offset:224
	ds_read_b128 v[150:153], v158 offset:192
	ds_read_b128 v[154:157], v158 offset:160
	ds_read_b128 v[158:161], v158 offset:128
	s_waitcnt lgkmcnt(3)
	v_pk_mul_f32 v[60:61], v[60:61], v[146:147]
	s_waitcnt lgkmcnt(2)
	v_pk_mul_f32 v[56:57], v[56:57], v[150:151]
	s_waitcnt lgkmcnt(1)
	v_pk_mul_f32 v[52:53], v[52:53], v[154:155]
	v_pk_mul_f32 v[62:63], v[62:63], v[148:149]
	v_pk_mul_f32 v[58:59], v[58:59], v[152:153]
	v_pk_mul_f32 v[54:55], v[54:55], v[156:157]
	s_waitcnt lgkmcnt(0)
	v_pk_mul_f32 v[50:51], v[50:51], v[160:161]
	v_pk_mul_f32 v[48:49], v[48:49], v[158:159]
	v_pk_mul_f32 v[44:45], v[44:45], v[146:147]
	v_pk_mul_f32 v[40:41], v[40:41], v[150:151]
	v_pk_mul_f32 v[36:37], v[36:37], v[154:155]
	v_pk_mul_f32 v[46:47], v[46:47], v[148:149]
	v_pk_mul_f32 v[42:43], v[42:43], v[152:153]
	v_pk_mul_f32 v[38:39], v[38:39], v[156:157]
	v_pk_mul_f32 v[34:35], v[34:35], v[160:161]
	v_pk_mul_f32 v[32:33], v[32:33], v[158:159]
	v_pk_mul_f32 v[28:29], v[28:29], v[146:147]
	v_pk_mul_f32 v[24:25], v[24:25], v[150:151]
	v_pk_mul_f32 v[20:21], v[20:21], v[154:155]
	v_pk_mul_f32 v[30:31], v[30:31], v[148:149]
	v_pk_mul_f32 v[26:27], v[26:27], v[152:153]
	v_pk_mul_f32 v[22:23], v[22:23], v[156:157]
	v_pk_mul_f32 v[18:19], v[18:19], v[160:161]
	v_pk_mul_f32 v[16:17], v[16:17], v[158:159]
	v_pk_mul_f32 v[12:13], v[12:13], v[146:147]
	v_pk_mul_f32 v[8:9], v[8:9], v[150:151]
	v_pk_mul_f32 v[4:5], v[4:5], v[154:155]
	v_pk_mul_f32 v[14:15], v[14:15], v[148:149]
	v_pk_mul_f32 v[10:11], v[10:11], v[152:153]
	v_pk_mul_f32 v[6:7], v[6:7], v[156:157]
	v_pk_mul_f32 v[2:3], v[2:3], v[160:161]
	v_pk_mul_f32 v[0:1], v[0:1], v[158:159]
	s_branch .LBB0_749
.Lresc_743:
	s_and_saveexec_b64 s[10:11], s[4:5]
	ds_write_b32 v194, v217 offset:128
	s_or_b64 exec, exec, s[10:11]
	s_waitcnt lgkmcnt(0)
	v_add_u32_e32 v163, v192, v144
	ds_read_b128 v[164:167], v163 offset:224
	ds_read_b128 v[168:171], v163 offset:192
	ds_read_b128 v[212:215], v163 offset:160
	ds_read_b128 v[218:221], v163 offset:128
	s_waitcnt lgkmcnt(3)
	v_pk_mul_f32 v[60:61], v[60:61], v[164:165]
	s_waitcnt lgkmcnt(2)
	v_pk_mul_f32 v[56:57], v[56:57], v[168:169]
	s_waitcnt lgkmcnt(1)
	v_pk_mul_f32 v[52:53], v[52:53], v[212:213]
	v_pk_mul_f32 v[62:63], v[62:63], v[166:167]
	v_pk_mul_f32 v[58:59], v[58:59], v[170:171]
	v_pk_mul_f32 v[54:55], v[54:55], v[214:215]
	s_waitcnt lgkmcnt(0)
	v_pk_mul_f32 v[50:51], v[50:51], v[220:221]
	v_pk_mul_f32 v[48:49], v[48:49], v[218:219]
	v_pk_mul_f32 v[44:45], v[44:45], v[164:165]
	v_pk_mul_f32 v[40:41], v[40:41], v[168:169]
	v_pk_mul_f32 v[36:37], v[36:37], v[212:213]
	v_pk_mul_f32 v[46:47], v[46:47], v[166:167]
	v_pk_mul_f32 v[42:43], v[42:43], v[170:171]
	v_pk_mul_f32 v[38:39], v[38:39], v[214:215]
	v_pk_mul_f32 v[34:35], v[34:35], v[220:221]
	v_pk_mul_f32 v[32:33], v[32:33], v[218:219]
	v_pk_mul_f32 v[28:29], v[28:29], v[164:165]
	v_pk_mul_f32 v[24:25], v[24:25], v[168:169]
	v_pk_mul_f32 v[20:21], v[20:21], v[212:213]
	v_pk_mul_f32 v[30:31], v[30:31], v[166:167]
	v_pk_mul_f32 v[26:27], v[26:27], v[170:171]
	v_pk_mul_f32 v[22:23], v[22:23], v[214:215]
	v_pk_mul_f32 v[18:19], v[18:19], v[220:221]
	v_pk_mul_f32 v[16:17], v[16:17], v[218:219]
	v_pk_mul_f32 v[12:13], v[12:13], v[164:165]
	v_pk_mul_f32 v[8:9], v[8:9], v[168:169]
	v_pk_mul_f32 v[4:5], v[4:5], v[212:213]
	v_pk_mul_f32 v[14:15], v[14:15], v[166:167]
	v_pk_mul_f32 v[10:11], v[10:11], v[170:171]
	v_pk_mul_f32 v[6:7], v[6:7], v[214:215]
	v_pk_mul_f32 v[2:3], v[2:3], v[220:221]
	v_pk_mul_f32 v[0:1], v[0:1], v[218:219]
	s_branch .LBB0_743

.LBB0_762:
	ds_read_b128 v[64:67], v189 offset:49152
	ds_read_b128 v[68:71], v189 offset:57344
	ds_read_b128 v[236:239], v191 offset:49152
	ds_read_b128 v[240:243], v191 offset:57344
	ds_read_b128 v[244:247], v193 offset:49152
	ds_read_b128 v[248:251], v193 offset:57344
	s_add_i32 s9, s24, -1
	s_cmp_lt_u32 s9, 3
	s_cselect_b32 s100, s46, s68
	s_add_i32 s100, s100, s8
	s_ashr_i32 s101, s100, 31
	s_mul_hi_u32 s7, s100, s40
	s_mul_i32 s6, s100, s41
	s_add_u32 s7, s7, s6
	s_mul_i32 s6, s101, s40
	s_add_u32 s7, s7, s6
	s_mul_i32 s6, s100, s40
	s_lshl_b64 s[6:7], s[6:7], 1
	s_add_i32 s0, 0, 0x12800
	s_waitcnt lgkmcnt(5)
	v_mfma_f32_32x32x16_bf16 v[80:95], v[64:67], v[124:127], 0
	v_exp_f32_e32 v140, v140
	v_exp_f32_e32 v141, v141
	v_add_u32_e32 v211, s0, v198
	s_waitcnt lgkmcnt(4)
	v_mfma_f32_32x32x16_bf16 v[64:79], v[68:71], v[124:127], 0
	v_exp_f32_e32 v138, v138
	v_exp_f32_e32 v139, v139
	v_add_u32_e32 v210, s0, v200
	s_waitcnt lgkmcnt(3)
	v_mfma_f32_32x32x16_bf16 v[80:95], v[236:239], v[120:123], v[80:95]
	ds_read_b128 v[236:239], v195 offset:49152
	v_exp_f32_e32 v214, v130
	v_exp_f32_e32 v215, v131
	v_add_u32_e32 v216, s0, v202
	s_waitcnt lgkmcnt(3)
	v_mfma_f32_32x32x16_bf16 v[64:79], v[240:243], v[120:123], v[64:79]
	ds_read_b128 v[240:243], v195 offset:57344
	v_exp_f32_e32 v142, v142
	v_exp_f32_e32 v143, v143
	v_add_u32_e32 v217, s0, v204
	s_waitcnt lgkmcnt(3)
	v_mfma_f32_32x32x16_bf16 v[80:95], v[244:247], v[116:119], v[80:95]
	ds_read_b128 v[244:247], v196 offset:49152
	v_exp_f32_e32 v136, v136
	v_exp_f32_e32 v137, v137
	v_cvt_pk_bf16_f32 v130, v156, v158
	s_waitcnt lgkmcnt(3)
	v_mfma_f32_32x32x16_bf16 v[64:79], v[248:251], v[116:119], v[64:79]
	ds_read_b128 v[248:251], v196 offset:57344
	v_exp_f32_e32 v212, v132
	v_exp_f32_e32 v213, v133
	v_cvt_pk_bf16_f32 v131, v154, v155
	s_waitcnt lgkmcnt(3)
	v_mfma_f32_32x32x16_bf16 v[80:95], v[236:239], v[112:115], v[80:95]
	ds_read_b128 v[236:239], v194 offset:49152
	v_exp_f32_e32 v220, v128
	v_add_f32_e32 v128, 0, v159
	v_add_f32_e32 v128, v161, v128
	v_add_f32_e32 v128, v157, v128
	s_waitcnt lgkmcnt(3)
	v_mfma_f32_32x32x16_bf16 v[64:79], v[240:243], v[112:115], v[64:79]
	ds_read_b128 v[240:243], v194 offset:57344
	v_add_f32_e32 v128, v160, v128
	v_add_f32_e32 v128, v156, v128
	v_add_f32_e32 v128, v158, v128
	v_add_f32_e32 v128, v154, v128
	v_add_f32_e32 v128, v155, v128
	s_waitcnt lgkmcnt(3)
	v_mfma_f32_32x32x16_bf16 v[80:95], v[244:247], v[108:111], v[80:95]
	ds_read_b128 v[244:247], v192 offset:49152
	v_add_f32_e32 v128, v151, v128
	v_add_f32_e32 v128, v153, v128
	v_add_f32_e32 v128, v150, v128
	v_add_f32_e32 v128, v152, v128
	v_add_f32_e32 v128, v147, v128
	s_waitcnt lgkmcnt(3)
	v_mfma_f32_32x32x16_bf16 v[64:79], v[248:251], v[108:111], v[64:79]
	ds_read_b128 v[248:251], v192 offset:57344
	v_add_f32_e32 v128, v149, v128
	v_add_f32_e32 v128, v146, v128
	v_add_f32_e32 v128, v148, v128
	v_add_f32_e32 v128, v140, v128
	v_add_f32_e32 v128, v141, v128
	s_waitcnt lgkmcnt(3)
	v_mfma_f32_32x32x16_bf16 v[80:95], v[236:239], v[104:107], v[80:95]
	ds_read_b128 v[236:239], v190 offset:49152
	v_add_f32_e32 v128, v138, v128
	v_add_f32_e32 v128, v139, v128
	v_add_f32_e32 v128, v212, v128
	v_exp_f32_e32 v221, v129
	s_waitcnt lgkmcnt(3)
	v_mfma_f32_32x32x16_bf16 v[64:79], v[240:243], v[104:107], v[64:79]
	ds_read_b128 v[240:243], v190 offset:57344
	v_add_f32_e32 v128, v213, v128
	v_add_f32_e32 v128, v214, v128
	v_add_f32_e32 v128, v215, v128
	v_add_f32_e32 v128, v220, v128
	v_add_f32_e32 v128, v221, v128
	s_waitcnt lgkmcnt(3)
	v_mfma_f32_32x32x16_bf16 v[80:95], v[244:247], v[100:103], v[80:95]
	ds_read_b128 v[244:247], v211
	v_exp_f32_e32 v223, v134
	v_add_f32_e32 v128, v142, v128
	v_exp_f32_e32 v224, v135
	s_waitcnt lgkmcnt(3)
	v_mfma_f32_32x32x16_bf16 v[64:79], v[248:251], v[100:103], v[64:79]
	v_add_f32_e32 v128, v143, v128
	v_add_f32_e32 v128, v136, v128
	v_add_f32_e32 v128, v137, v128
	v_add_f32_e32 v128, v223, v128
	v_add_f32_e32 v218, v224, v128
	s_waitcnt lgkmcnt(2)
	v_mfma_f32_32x32x16_bf16 v[80:95], v[236:239], v[96:99], v[80:95]
	ds_read_b128 v[236:239], v211 offset:4096
	ds_read_b128 v[248:251], v182
	v_mov_b32_e32 v219, v218
	v_cvt_pk_bf16_f32 v128, v159, v161
	v_cvt_pk_bf16_f32 v129, v157, v160
	v_cvt_pk_bf16_f32 v132, v151, v153
	v_cvt_pk_bf16_f32 v133, v150, v152
	s_waitcnt lgkmcnt(3)
	v_mfma_f32_32x32x16_bf16 v[64:79], v[240:243], v[96:99], v[64:79]
	ds_read_b128 v[240:243], v210
	v_cvt_pk_bf16_f32 v134, v147, v149
	v_cvt_pk_bf16_f32 v135, v146, v148
	v_cvt_pk_bf16_f32 v154, v140, v141
	v_cvt_pk_bf16_f32 v155, v138, v139
	v_cvt_pk_bf16_f32 v156, v212, v213
	s_waitcnt lgkmcnt(1)
	v_mfma_f32_32x32x16_bf16 v[80:95], v[244:247], v[248:251], v[80:95]
	v_cvt_pk_bf16_f32 v157, v214, v215
	v_cvt_pk_bf16_f32 v220, v220, v221
	v_cvt_pk_bf16_f32 v221, v142, v143
	v_cvt_pk_bf16_f32 v222, v136, v137
	v_permlane32_swap_b32_e32 v218, v219
	v_mfma_f32_32x32x16_bf16 v[64:79], v[236:239], v[248:251], v[64:79]
	ds_read_b128 v[248:251], v210 offset:4096
	ds_read_b128 v[244:247], v182 offset:1024
	ds_read_b128 v[236:239], v216
	v_permlane32_swap_b32_e32 v128, v130
	v_cvt_pk_bf16_f32 v223, v223, v224
	v_permlane32_swap_b32_e32 v220, v222
	v_permlane32_swap_b32_e32 v129, v131
	v_permlane32_swap_b32_e32 v132, v134
	s_waitcnt lgkmcnt(1)
	v_mfma_f32_32x32x16_bf16 v[80:95], v[240:243], v[244:247], v[80:95]
	v_permlane32_swap_b32_e32 v133, v135
	v_permlane32_swap_b32_e32 v154, v156
	v_permlane32_swap_b32_e32 v155, v157
	v_permlane32_swap_b32_e32 v221, v223
	v_lshl_add_u64 v[136:137], s[6:7], 0, v[162:163]
	v_mfma_f32_32x32x16_bf16 v[64:79], v[248:251], v[244:247], v[64:79]
	ds_read_b128 v[244:247], v216 offset:4096
	ds_read_b128 v[240:243], v182 offset:2048
	ds_read_b128 v[248:251], v217
	v_lshl_add_u64 v[140:141], s[6:7], 0, v[166:167]
	v_lshl_add_u64 v[146:147], s[6:7], 0, v[168:169]
	v_lshl_add_u64 v[150:151], s[6:7], 0, v[170:171]
	v_lshl_add_u64 v[158:159], s[100:101], 0, v[164:165]
	v_mad_u64_u32 v[160:161], s[100:101], v158, s3, v[172:173]
	s_waitcnt lgkmcnt(1)
	v_mfma_f32_32x32x16_bf16 v[80:95], v[236:239], v[240:243], v[80:95]
	v_mad_i32_i24 v161, v159, s3, v161
	v_mfma_f32_32x32x16_bf16 v[64:79], v[244:247], v[240:243], v[64:79]
	ds_read_b128 v[240:243], v217 offset:4096
	ds_read_b128 v[236:239], v182 offset:3072
	ds_read_b64_tr_b16 v[224:225], v181 offset:0
	ds_read_b64_tr_b16 v[226:227], v181 offset:0x800
	ds_read_b64_tr_b16 v[232:233], v181 offset:0x1000
	ds_read_b64_tr_b16 v[234:235], v181 offset:0x1800
	s_waitcnt lgkmcnt(4)
	v_mfma_f32_32x32x16_bf16 v[80:95], v[248:251], v[236:239], v[80:95]
	v_mfma_f32_32x32x16_bf16 v[64:79], v[240:243], v[236:239], v[64:79]
	ds_read_b64_tr_b16 v[236:237], v181 offset:0x2000
	ds_read_b64_tr_b16 v[238:239], v181 offset:0x2800
	ds_read_b64_tr_b16 v[240:241], v181 offset:0x3000
	ds_read_b64_tr_b16 v[242:243], v181 offset:0x3800
	ds_read_b64_tr_b16 v[212:213], v181 offset:0x200
	ds_read_b64_tr_b16 v[214:215], v181 offset:0xa00
	global_load_dwordx4 v[136:139], v[136:137], off
	global_load_dwordx4 v[140:143], v[140:141], off
	global_load_dwordx4 v[146:149], v[146:147], off
	global_load_dwordx4 v[150:153], v[150:151], off
	global_load_dwordx4 v[158:161], v[160:161], off
	s_waitcnt lgkmcnt(8)
	v_mfma_f32_32x32x16_bf16 v[0:15], v[128:131], v[224:227], v[0:15]
	ds_read_b64_tr_b16 v[224:225], v181 offset:0x1200
	ds_read_b64_tr_b16 v[226:227], v181 offset:0x1a00
	v_max_f32_e32 v250, v81, v81
	v_max_f32_e32 v251, v80, v80
	v_max_f32_e32 v250, v251, v250
	v_max3_f32 v250, v250, v82, v83
	v_max3_f32 v250, v250, v84, v85
	s_waitcnt lgkmcnt(8)
	v_mfma_f32_32x32x16_bf16 v[0:15], v[132:135], v[232:235], v[0:15]
	ds_read_b64_tr_b16 v[232:233], v181 offset:0x2200
	ds_read_b64_tr_b16 v[234:235], v181 offset:0x2a00
	v_max3_f32 v250, v250, v86, v87
	v_max3_f32 v250, v250, v88, v89
	v_max3_f32 v250, v250, v90, v91
	v_max3_f32 v250, v250, v92, v93
	v_max3_f32 v250, v250, v94, v95
	s_waitcnt lgkmcnt(8)
	v_mfma_f32_32x32x16_bf16 v[0:15], v[154:157], v[236:239], v[0:15]
	ds_read_b64_tr_b16 v[236:237], v181 offset:0x3200
	ds_read_b64_tr_b16 v[238:239], v181 offset:0x3a00
	v_max3_f32 v250, v250, v64, v65
	v_max3_f32 v250, v250, v66, v67
	v_max3_f32 v250, v250, v68, v69
	v_max3_f32 v250, v250, v70, v71
	v_max3_f32 v250, v250, v72, v73
	s_waitcnt lgkmcnt(8)
	v_mfma_f32_32x32x16_bf16 v[0:15], v[220:223], v[240:243], v[0:15]
	ds_read_b64_tr_b16 v[240:241], v181 offset:0x400
	ds_read_b64_tr_b16 v[242:243], v181 offset:0xc00
	v_max3_f32 v250, v250, v74, v75
	v_max3_f32 v250, v250, v76, v77
	v_max3_f32 v250, v250, v78, v79
	v_mov_b32_e32 v251, v250
	s_nop 1
	v_permlane32_swap_b32_e32 v250, v251
	s_waitcnt lgkmcnt(8)
	v_mfma_f32_32x32x16_bf16 v[48:63], v[128:131], v[212:215], v[48:63]
	ds_read_b64_tr_b16 v[212:213], v181 offset:0x1400
	ds_read_b64_tr_b16 v[214:215], v181 offset:0x1c00
	v_max_f32_e32 v251, v251, v251
	v_max_f32_e32 v250, v250, v250
	v_max_f32_e32 v250, v250, v251
	v_sub_f32_e32 v251, v250, v207
	v_cmp_ge_f32_e32 vcc, s94, v251
	s_waitcnt lgkmcnt(8)
	v_mfma_f32_32x32x16_bf16 v[48:63], v[132:135], v[224:227], v[48:63]
	ds_read_b64_tr_b16 v[224:225], v181 offset:0x2400
	ds_read_b64_tr_b16 v[226:227], v181 offset:0x2c00
	v_max_f32_e32 v251, v207, v207
	v_max_f32_e32 v250, v251, v250
	v_sub_f32_e32 v251, v207, v250
	v_mul_f32_e32 v251, 0x3dd53b94, v251
	s_waitcnt lgkmcnt(8)
	v_mfma_f32_32x32x16_bf16 v[48:63], v[154:157], v[232:235], v[48:63]
	ds_read_b64_tr_b16 v[232:233], v181 offset:0x3400
	ds_read_b64_tr_b16 v[234:235], v181 offset:0x3c00
	v_exp_f32_e32 v251, v251
	s_waitcnt lgkmcnt(8)
	v_mfma_f32_32x32x16_bf16 v[48:63], v[220:223], v[236:239], v[48:63]
	ds_read_b64_tr_b16 v[236:237], v181 offset:0x600
	ds_read_b64_tr_b16 v[238:239], v181 offset:0xe00
	s_waitcnt lgkmcnt(8)
	v_mfma_f32_32x32x16_bf16 v[32:47], v[128:131], v[240:243], v[32:47]
	ds_read_b64_tr_b16 v[240:241], v181 offset:0x1600
	ds_read_b64_tr_b16 v[242:243], v181 offset:0x1e00
	s_waitcnt lgkmcnt(8)
	v_mfma_f32_32x32x16_bf16 v[32:47], v[132:135], v[212:215], v[32:47]
	ds_read_b64_tr_b16 v[212:213], v181 offset:0x2600
	ds_read_b64_tr_b16 v[214:215], v181 offset:0x2e00
	s_waitcnt lgkmcnt(8)
	v_mfma_f32_32x32x16_bf16 v[32:47], v[154:157], v[224:227], v[32:47]
	ds_read_b64_tr_b16 v[224:225], v181 offset:0x3600
	ds_read_b64_tr_b16 v[226:227], v181 offset:0x3e00
	s_waitcnt lgkmcnt(8)
	v_mfma_f32_32x32x16_bf16 v[32:47], v[220:223], v[232:235], v[32:47]
	s_waitcnt lgkmcnt(6)
	v_mfma_f32_32x32x16_bf16 v[16:31], v[128:131], v[236:239], v[16:31]
	s_waitcnt lgkmcnt(4)
	v_mfma_f32_32x32x16_bf16 v[16:31], v[132:135], v[240:243], v[16:31]
	s_waitcnt lgkmcnt(2)
	v_mfma_f32_32x32x16_bf16 v[16:31], v[154:157], v[212:215], v[16:31]
	s_waitcnt lgkmcnt(0)
	v_mfma_f32_32x32x16_bf16 v[16:31], v[220:223], v[224:227], v[16:31]
	s_cmp_eq_u64 vcc, exec
	s_cselect_b64 s[6:7], -1, 0
	s_barrier
	s_waitcnt vmcnt(0)
	v_cndmask_b32_e64 v220, v251, 1.0, s[6:7]
	v_add_u32_e32 v129, 0x10800, v208
	ds_write_b128 v187, v[146:149] offset:32768
	ds_write_b128 v188, v[150:153] offset:32768
	ds_write_b128 v129, v[158:161]
	ds_write_b128 v185, v[136:139]
	ds_write_b128 v186, v[140:143]
	s_nop 0
	s_nop 0
	s_nop 0
	s_nop 0
	s_nop 0
	s_and_b64 vcc, exec, s[6:7]
	s_cbranch_vccz .Lresc_766
.LBB0_766:
	v_cndmask_b32_e64 v207, v250, v207, s[6:7]
	v_mul_f32_e32 v146, 0xbdd53b94, v207
	v_fmamk_f32 v80, v80, 0x3dd53b94, v146
	v_exp_f32_e32 v128, v80
	v_fmamk_f32 v81, v81, 0x3dd53b94, v146
	v_fmamk_f32 v82, v82, 0x3dd53b94, v146
	v_fmamk_f32 v83, v83, 0x3dd53b94, v146
	v_fmamk_f32 v84, v84, 0x3dd53b94, v146
	v_fmamk_f32 v85, v85, 0x3dd53b94, v146
	v_fmamk_f32 v86, v86, 0x3dd53b94, v146
	v_fmamk_f32 v87, v87, 0x3dd53b94, v146
	v_fmamk_f32 v88, v88, 0x3dd53b94, v146
	v_fmamk_f32 v89, v89, 0x3dd53b94, v146
	v_fmamk_f32 v90, v90, 0x3dd53b94, v146
	v_fmamk_f32 v91, v91, 0x3dd53b94, v146
	v_fmamk_f32 v92, v92, 0x3dd53b94, v146
	v_fmamk_f32 v93, v93, 0x3dd53b94, v146
	v_fmamk_f32 v94, v94, 0x3dd53b94, v146
	v_fmamk_f32 v95, v95, 0x3dd53b94, v146
	v_fmamk_f32 v155, v64, 0x3dd53b94, v146
	v_fmamk_f32 v156, v65, 0x3dd53b94, v146
	v_fmamk_f32 v157, v66, 0x3dd53b94, v146
	v_fmamk_f32 v158, v67, 0x3dd53b94, v146
	v_fmamk_f32 v159, v68, 0x3dd53b94, v146
	v_fmamk_f32 v148, v69, 0x3dd53b94, v146
	v_fmamk_f32 v149, v70, 0x3dd53b94, v146
	v_fmamk_f32 v150, v71, 0x3dd53b94, v146
	v_fmamk_f32 v151, v72, 0x3dd53b94, v146
	v_fmamk_f32 v152, v73, 0x3dd53b94, v146
	v_fmamk_f32 v153, v74, 0x3dd53b94, v146
	v_fmamk_f32 v154, v75, 0x3dd53b94, v146
	v_fmamk_f32 v147, v76, 0x3dd53b94, v146
	v_exp_f32_e32 v143, v81
	v_exp_f32_e32 v129, v82
	v_exp_f32_e32 v142, v83
	v_exp_f32_e32 v130, v84
	v_exp_f32_e32 v141, v85
	v_exp_f32_e32 v131, v86
	v_exp_f32_e32 v140, v87
	v_exp_f32_e32 v132, v88
	v_exp_f32_e32 v139, v89
	v_exp_f32_e32 v133, v90
	v_exp_f32_e32 v138, v91
	v_exp_f32_e32 v134, v92
	v_exp_f32_e32 v137, v93
	v_exp_f32_e32 v135, v94
	v_exp_f32_e32 v136, v95
	v_fmamk_f32 v160, v77, 0x3dd53b94, v146
	v_fmamk_f32 v161, v78, 0x3dd53b94, v146
	v_fmac_f32_e32 v146, 0x3dd53b94, v79
	s_waitcnt lgkmcnt(2)
	s_barrier
	ds_read_b128 v[64:67], v189 offset:32768
	ds_read_b128 v[68:71], v189 offset:40960
	ds_read_b128 v[240:243], v191 offset:32768
	ds_read_b128 v[244:247], v191 offset:40960
	ds_read_b128 v[248:251], v193 offset:32768
	s_cmp_lt_u32 s9, 2
	s_cselect_b32 s100, s46, s68
	s_add_i32 s100, s100, s8
	s_add_i32 s100, s100, 64
	s_ashr_i32 s101, s100, 31
	s_mul_hi_u32 s7, s100, s40
	s_mul_i32 s6, s100, s41
	s_add_u32 s7, s7, s6
	s_mul_i32 s6, s101, s40
	s_add_u32 s7, s7, s6
	s_mul_i32 s6, s100, s40
	s_lshl_b64 s[6:7], s[6:7], 1
	s_waitcnt lgkmcnt(4)
	v_mfma_f32_32x32x16_bf16 v[80:95], v[64:67], v[124:127], 0
	v_exp_f32_e32 v212, v154
	v_add_f32_e32 v154, 0, v128
	v_add_f32_e32 v154, v143, v154
	v_add_f32_e32 v154, v129, v154
	s_waitcnt lgkmcnt(3)
	v_mfma_f32_32x32x16_bf16 v[64:79], v[68:71], v[124:127], 0
	v_add_f32_e32 v154, v142, v154
	v_add_f32_e32 v154, v130, v154
	v_add_f32_e32 v154, v141, v154
	v_add_f32_e32 v154, v131, v154
	v_add_f32_e32 v154, v140, v154
	s_waitcnt lgkmcnt(2)
	v_mfma_f32_32x32x16_bf16 v[80:95], v[240:243], v[120:123], v[80:95]
	ds_read_b128 v[240:243], v193 offset:40960
	v_add_f32_e32 v154, v132, v154
	v_add_f32_e32 v154, v139, v154
	v_add_f32_e32 v154, v133, v154
	v_add_f32_e32 v154, v138, v154
	v_add_f32_e32 v154, v134, v154
	s_waitcnt lgkmcnt(2)
	v_mfma_f32_32x32x16_bf16 v[64:79], v[244:247], v[120:123], v[64:79]
	ds_read_b128 v[244:247], v195 offset:32768
	v_exp_f32_e32 v155, v155
	v_exp_f32_e32 v156, v156
	v_add_f32_e32 v154, v137, v154
	s_waitcnt lgkmcnt(2)
	v_mfma_f32_32x32x16_bf16 v[80:95], v[248:251], v[116:119], v[80:95]
	ds_read_b128 v[248:251], v195 offset:40960
	v_exp_f32_e32 v157, v157
	v_add_f32_e32 v154, v135, v154
	v_exp_f32_e32 v158, v158
	s_waitcnt lgkmcnt(2)
	v_mfma_f32_32x32x16_bf16 v[64:79], v[240:243], v[116:119], v[64:79]
	ds_read_b128 v[240:243], v196 offset:32768
	v_add_f32_e32 v154, v136, v154
	v_exp_f32_e32 v159, v159
	v_add_f32_e32 v154, v155, v154
	v_add_f32_e32 v154, v156, v154
	s_waitcnt lgkmcnt(2)
	v_mfma_f32_32x32x16_bf16 v[80:95], v[244:247], v[112:115], v[80:95]
	ds_read_b128 v[244:247], v196 offset:40960
	v_exp_f32_e32 v148, v148
	v_exp_f32_e32 v149, v149
	v_add_f32_e32 v154, v157, v154
	s_waitcnt lgkmcnt(2)
	v_mfma_f32_32x32x16_bf16 v[64:79], v[248:251], v[112:115], v[64:79]
	ds_read_b128 v[248:251], v194 offset:32768
	v_exp_f32_e32 v150, v150
	v_add_f32_e32 v154, v158, v154
	v_exp_f32_e32 v151, v151
	s_waitcnt lgkmcnt(2)
	v_mfma_f32_32x32x16_bf16 v[80:95], v[240:243], v[108:111], v[80:95]
	ds_read_b128 v[240:243], v194 offset:40960
	v_add_f32_e32 v154, v159, v154
	v_exp_f32_e32 v152, v152
	v_add_f32_e32 v154, v148, v154
	v_add_f32_e32 v154, v149, v154
	s_waitcnt lgkmcnt(2)
	v_mfma_f32_32x32x16_bf16 v[64:79], v[244:247], v[108:111], v[64:79]
	ds_read_b128 v[244:247], v192 offset:32768
	v_exp_f32_e32 v153, v153
	v_add_f32_e32 v154, v150, v154
	v_exp_f32_e32 v147, v147
	s_waitcnt lgkmcnt(2)
	v_mfma_f32_32x32x16_bf16 v[80:95], v[248:251], v[104:107], v[80:95]
	ds_read_b128 v[248:251], v192 offset:40960
	v_add_f32_e32 v154, v151, v154
	v_exp_f32_e32 v160, v160
	v_add_f32_e32 v154, v152, v154
	v_add_f32_e32 v154, v153, v154
	s_waitcnt lgkmcnt(2)
	v_mfma_f32_32x32x16_bf16 v[64:79], v[240:243], v[104:107], v[64:79]
	ds_read_b128 v[240:243], v190 offset:32768
	v_exp_f32_e32 v161, v161
	v_exp_f32_e32 v146, v146
	v_add_f32_e32 v154, v212, v154
	s_waitcnt lgkmcnt(2)
	v_mfma_f32_32x32x16_bf16 v[80:95], v[244:247], v[100:103], v[80:95]
	ds_read_b128 v[244:247], v190 offset:40960
	v_add_f32_e32 v154, v147, v154
	v_add_f32_e32 v154, v160, v154
	v_add_f32_e32 v154, v161, v154
	v_cvt_pk_bf16_f32 v128, v128, v143
	v_cvt_pk_bf16_f32 v129, v129, v142
	s_waitcnt lgkmcnt(2)
	v_mfma_f32_32x32x16_bf16 v[64:79], v[248:251], v[100:103], v[64:79]
	ds_read_b128 v[248:251], v199
	v_cvt_pk_bf16_f32 v130, v130, v141
	v_cvt_pk_bf16_f32 v131, v131, v140
	v_cvt_pk_bf16_f32 v132, v132, v139
	v_cvt_pk_bf16_f32 v133, v133, v138
	v_add_f32_e32 v222, v146, v154
	s_waitcnt lgkmcnt(2)
	v_mfma_f32_32x32x16_bf16 v[80:95], v[240:243], v[96:99], v[80:95]
	v_mov_b32_e32 v223, v222
	s_nop 1
	v_permlane32_swap_b32_e32 v222, v223
	v_permlane32_swap_b32_e32 v128, v130
	v_cvt_pk_bf16_f32 v134, v134, v137
	v_cvt_pk_bf16_f32 v135, v135, v136
	s_waitcnt lgkmcnt(1)
	v_mfma_f32_32x32x16_bf16 v[64:79], v[244:247], v[96:99], v[64:79]
	ds_read_b128 v[244:247], v199 offset:4096
	ds_read_b128 v[240:243], v182
	v_cvt_pk_bf16_f32 v154, v155, v156
	v_cvt_pk_bf16_f32 v155, v157, v158
	v_cvt_pk_bf16_f32 v156, v159, v148
	v_cvt_pk_bf16_f32 v157, v149, v150
	v_cvt_pk_bf16_f32 v224, v151, v152
	s_waitcnt lgkmcnt(0)
	v_mfma_f32_32x32x16_bf16 v[80:95], v[248:251], v[240:243], v[80:95]
	ds_read_b128 v[248:251], v201
	v_cvt_pk_bf16_f32 v225, v153, v212
	v_cvt_pk_bf16_f32 v226, v147, v160
	v_cvt_pk_bf16_f32 v227, v161, v146
	v_permlane32_swap_b32_e32 v129, v131
	v_permlane32_swap_b32_e32 v132, v134
	v_mfma_f32_32x32x16_bf16 v[64:79], v[244:247], v[240:243], v[64:79]
	ds_read_b128 v[244:247], v201 offset:4096
	ds_read_b128 v[240:243], v182 offset:1024
	v_permlane32_swap_b32_e32 v133, v135
	v_permlane32_swap_b32_e32 v154, v156
	v_permlane32_swap_b32_e32 v155, v157
	v_permlane32_swap_b32_e32 v224, v226
	v_permlane32_swap_b32_e32 v225, v227
	s_waitcnt lgkmcnt(0)
	v_mfma_f32_32x32x16_bf16 v[80:95], v[248:251], v[240:243], v[80:95]
	ds_read_b128 v[248:251], v203
	v_lshl_add_u64 v[136:137], s[6:7], 0, v[162:163]
	v_lshl_add_u64 v[140:141], s[6:7], 0, v[166:167]
	v_lshl_add_u64 v[146:147], s[6:7], 0, v[168:169]
	v_lshl_add_u64 v[150:151], s[6:7], 0, v[170:171]
	v_lshl_add_u64 v[158:159], s[100:101], 0, v[164:165]
	v_mfma_f32_32x32x16_bf16 v[64:79], v[244:247], v[240:243], v[64:79]
	ds_read_b128 v[244:247], v203 offset:4096
	ds_read_b128 v[240:243], v182 offset:2048
	v_mad_u64_u32 v[160:161], s[100:101], v158, s3, v[172:173]
	v_mad_i32_i24 v161, v159, s3, v161
	s_waitcnt lgkmcnt(0)
	v_mfma_f32_32x32x16_bf16 v[80:95], v[248:251], v[240:243], v[80:95]
	ds_read_b128 v[248:251], v205
	v_mfma_f32_32x32x16_bf16 v[64:79], v[244:247], v[240:243], v[64:79]
	ds_read_b128 v[244:247], v205 offset:4096
	ds_read_b128 v[240:243], v182 offset:3072
	ds_read_b64_tr_b16 v[232:233], v184 offset:0
	ds_read_b64_tr_b16 v[234:235], v184 offset:0x800
	ds_read_b64_tr_b16 v[236:237], v184 offset:0x1000
	ds_read_b64_tr_b16 v[238:239], v184 offset:0x1800
	s_waitcnt lgkmcnt(4)
	v_mfma_f32_32x32x16_bf16 v[80:95], v[248:251], v[240:243], v[80:95]
	v_mfma_f32_32x32x16_bf16 v[64:79], v[244:247], v[240:243], v[64:79]
	ds_read_b64_tr_b16 v[240:241], v184 offset:0x2000
	ds_read_b64_tr_b16 v[242:243], v184 offset:0x2800
	ds_read_b64_tr_b16 v[244:245], v184 offset:0x3000
	ds_read_b64_tr_b16 v[246:247], v184 offset:0x3800
	global_load_dwordx4 v[136:139], v[136:137], off
	global_load_dwordx4 v[140:143], v[140:141], off
	global_load_dwordx4 v[146:149], v[146:147], off
	global_load_dwordx4 v[150:153], v[150:151], off
	global_load_dwordx4 v[158:161], v[160:161], off
	s_waitcnt lgkmcnt(6)
	v_mfma_f32_32x32x16_bf16 v[0:15], v[128:131], v[232:235], v[0:15]
	ds_read_b64_tr_b16 v[232:233], v184 offset:0x200
	ds_read_b64_tr_b16 v[234:235], v184 offset:0xa00
	s_waitcnt lgkmcnt(6)
	v_mfma_f32_32x32x16_bf16 v[0:15], v[132:135], v[236:239], v[0:15]
	ds_read_b64_tr_b16 v[236:237], v184 offset:0x1200
	ds_read_b64_tr_b16 v[238:239], v184 offset:0x1a00
	v_max_f32_e32 v250, v81, v81
	v_max_f32_e32 v251, v80, v80
	v_max_f32_e32 v250, v251, v250
	v_max3_f32 v250, v250, v82, v83
	v_max3_f32 v250, v250, v84, v85
	s_waitcnt lgkmcnt(6)
	v_mfma_f32_32x32x16_bf16 v[0:15], v[154:157], v[240:243], v[0:15]
	ds_read_b64_tr_b16 v[240:241], v184 offset:0x2200
	ds_read_b64_tr_b16 v[242:243], v184 offset:0x2a00
	v_max3_f32 v250, v250, v86, v87
	v_max3_f32 v250, v250, v88, v89
	v_max3_f32 v250, v250, v90, v91
	v_max3_f32 v250, v250, v92, v93
	v_max3_f32 v250, v250, v94, v95
	s_waitcnt lgkmcnt(6)
	v_mfma_f32_32x32x16_bf16 v[0:15], v[224:227], v[244:247], v[0:15]
	ds_read_b64_tr_b16 v[244:245], v184 offset:0x3200
	ds_read_b64_tr_b16 v[246:247], v184 offset:0x3a00
	v_max3_f32 v250, v250, v64, v65
	v_max3_f32 v250, v250, v66, v67
	v_max3_f32 v250, v250, v68, v69
	v_max3_f32 v250, v250, v70, v71
	v_max3_f32 v250, v250, v72, v73
	s_waitcnt lgkmcnt(6)
	v_mfma_f32_32x32x16_bf16 v[48:63], v[128:131], v[232:235], v[48:63]
	ds_read_b64_tr_b16 v[232:233], v184 offset:0x400
	ds_read_b64_tr_b16 v[234:235], v184 offset:0xc00
	v_max3_f32 v250, v250, v74, v75
	v_max3_f32 v250, v250, v76, v77
	v_max3_f32 v250, v250, v78, v79
	v_mov_b32_e32 v251, v250
	s_nop 1
	v_permlane32_swap_b32_e32 v250, v251
	s_waitcnt lgkmcnt(6)
	v_mfma_f32_32x32x16_bf16 v[48:63], v[132:135], v[236:239], v[48:63]
	ds_read_b64_tr_b16 v[236:237], v184 offset:0x1400
	ds_read_b64_tr_b16 v[238:239], v184 offset:0x1c00
	v_max_f32_e32 v251, v251, v251
	v_max_f32_e32 v250, v250, v250
	v_max_f32_e32 v250, v250, v251
	v_sub_f32_e32 v251, v250, v207
	v_cmp_ge_f32_e32 vcc, s94, v251
	s_waitcnt lgkmcnt(6)
	v_mfma_f32_32x32x16_bf16 v[48:63], v[154:157], v[240:243], v[48:63]
	ds_read_b64_tr_b16 v[240:241], v184 offset:0x2400
	ds_read_b64_tr_b16 v[242:243], v184 offset:0x2c00
	v_max_f32_e32 v251, v207, v207
	v_max_f32_e32 v250, v251, v250
	v_sub_f32_e32 v251, v207, v250
	v_mul_f32_e32 v251, 0x3dd53b94, v251
	s_waitcnt lgkmcnt(6)
	v_mfma_f32_32x32x16_bf16 v[48:63], v[224:227], v[244:247], v[48:63]
	ds_read_b64_tr_b16 v[244:245], v184 offset:0x3400
	ds_read_b64_tr_b16 v[246:247], v184 offset:0x3c00
	v_exp_f32_e32 v251, v251
	s_waitcnt lgkmcnt(6)
	v_mfma_f32_32x32x16_bf16 v[32:47], v[128:131], v[232:235], v[32:47]
	ds_read_b64_tr_b16 v[232:233], v184 offset:0x600
	ds_read_b64_tr_b16 v[234:235], v184 offset:0xe00
	s_waitcnt lgkmcnt(6)
	v_mfma_f32_32x32x16_bf16 v[32:47], v[132:135], v[236:239], v[32:47]
	ds_read_b64_tr_b16 v[236:237], v184 offset:0x1600
	ds_read_b64_tr_b16 v[238:239], v184 offset:0x1e00
	s_waitcnt lgkmcnt(6)
	v_mfma_f32_32x32x16_bf16 v[32:47], v[154:157], v[240:243], v[32:47]
	ds_read_b64_tr_b16 v[240:241], v184 offset:0x2600
	ds_read_b64_tr_b16 v[242:243], v184 offset:0x2e00
	s_waitcnt lgkmcnt(6)
	v_mfma_f32_32x32x16_bf16 v[32:47], v[224:227], v[244:247], v[32:47]
	ds_read_b64_tr_b16 v[244:245], v184 offset:0x3600
	ds_read_b64_tr_b16 v[246:247], v184 offset:0x3e00
	s_waitcnt lgkmcnt(6)
	v_mfma_f32_32x32x16_bf16 v[16:31], v[128:131], v[232:235], v[16:31]
	s_waitcnt lgkmcnt(4)
	v_mfma_f32_32x32x16_bf16 v[16:31], v[132:135], v[236:239], v[16:31]
	s_waitcnt lgkmcnt(2)
	v_mfma_f32_32x32x16_bf16 v[16:31], v[154:157], v[240:243], v[16:31]
	s_waitcnt lgkmcnt(0)
	v_mfma_f32_32x32x16_bf16 v[16:31], v[224:227], v[244:247], v[16:31]
	s_cmp_eq_u64 vcc, exec
	s_cselect_b64 s[6:7], -1, 0
	s_barrier
	s_waitcnt vmcnt(0)
	v_cndmask_b32_e64 v221, v251, 1.0, s[6:7]
	ds_write_b128 v187, v[146:149] offset:49152
	ds_write_b128 v188, v[150:153] offset:49152
	ds_write_b128 v209, v[158:161]
	ds_write_b128 v185, v[136:139] offset:16384
	ds_write_b128 v186, v[140:143] offset:16384
	s_nop 0
	s_nop 0
	s_nop 0
	s_nop 0
	s_nop 0
	s_and_b64 vcc, exec, s[6:7]
	s_cbranch_vccz .Lresc_770

.Lresc_770:
	s_and_saveexec_b64 s[0:1], s[4:5]
	ds_write_b32 v183, v221 offset:128
	s_or_b64 exec, exec, s[0:1]
	s_waitcnt lgkmcnt(0)
	v_add_u32_e32 v129, v180, v144
	ds_read_b128 v[130:133], v129 offset:224
	ds_read_b128 v[134:137], v129 offset:192
	ds_read_b128 v[138:141], v129 offset:160
	ds_read_b128 v[146:149], v129 offset:128
	s_waitcnt lgkmcnt(3)
	v_pk_mul_f32 v[12:13], v[12:13], v[130:131]
	s_waitcnt lgkmcnt(2)
	v_pk_mul_f32 v[8:9], v[8:9], v[134:135]
	s_waitcnt lgkmcnt(1)
	v_pk_mul_f32 v[4:5], v[4:5], v[138:139]
	v_pk_mul_f32 v[14:15], v[14:15], v[132:133]
	v_pk_mul_f32 v[10:11], v[10:11], v[136:137]
	v_pk_mul_f32 v[6:7], v[6:7], v[140:141]
	s_waitcnt lgkmcnt(0)
	v_pk_mul_f32 v[2:3], v[2:3], v[148:149]
	v_pk_mul_f32 v[0:1], v[0:1], v[146:147]
	v_pk_mul_f32 v[60:61], v[60:61], v[130:131]
	v_pk_mul_f32 v[56:57], v[56:57], v[134:135]
	v_pk_mul_f32 v[52:53], v[52:53], v[138:139]
	v_pk_mul_f32 v[62:63], v[62:63], v[132:133]
	v_pk_mul_f32 v[58:59], v[58:59], v[136:137]
	v_pk_mul_f32 v[54:55], v[54:55], v[140:141]
	v_pk_mul_f32 v[50:51], v[50:51], v[148:149]
	v_pk_mul_f32 v[48:49], v[48:49], v[146:147]
	v_pk_mul_f32 v[44:45], v[44:45], v[130:131]
	v_pk_mul_f32 v[40:41], v[40:41], v[134:135]
	v_pk_mul_f32 v[36:37], v[36:37], v[138:139]
	v_pk_mul_f32 v[46:47], v[46:47], v[132:133]
	v_pk_mul_f32 v[42:43], v[42:43], v[136:137]
	v_pk_mul_f32 v[38:39], v[38:39], v[140:141]
	v_pk_mul_f32 v[34:35], v[34:35], v[148:149]
	v_pk_mul_f32 v[32:33], v[32:33], v[146:147]
	v_pk_mul_f32 v[28:29], v[28:29], v[130:131]
	v_pk_mul_f32 v[24:25], v[24:25], v[134:135]
	v_pk_mul_f32 v[20:21], v[20:21], v[138:139]
	v_pk_mul_f32 v[30:31], v[30:31], v[132:133]
	v_pk_mul_f32 v[26:27], v[26:27], v[136:137]
	v_pk_mul_f32 v[22:23], v[22:23], v[140:141]
	v_pk_mul_f32 v[18:19], v[18:19], v[148:149]
	v_pk_mul_f32 v[16:17], v[16:17], v[146:147]
	s_branch .LBB0_770
.Lresc_766:
	s_and_saveexec_b64 s[0:1], s[4:5]
	ds_write_b32 v183, v220 offset:128
	s_or_b64 exec, exec, s[0:1]
	s_waitcnt lgkmcnt(0)
	v_add_u32_e32 v129, v180, v144
	ds_read_b128 v[130:133], v129 offset:224
	ds_read_b128 v[134:137], v129 offset:192
	ds_read_b128 v[138:141], v129 offset:160
	ds_read_b128 v[146:149], v129 offset:128
	s_waitcnt lgkmcnt(3)
	v_pk_mul_f32 v[12:13], v[12:13], v[130:131]
	s_waitcnt lgkmcnt(2)
	v_pk_mul_f32 v[8:9], v[8:9], v[134:135]
	s_waitcnt lgkmcnt(1)
	v_pk_mul_f32 v[4:5], v[4:5], v[138:139]
	v_pk_mul_f32 v[14:15], v[14:15], v[132:133]
	v_pk_mul_f32 v[10:11], v[10:11], v[136:137]
	v_pk_mul_f32 v[6:7], v[6:7], v[140:141]
	s_waitcnt lgkmcnt(0)
	v_pk_mul_f32 v[2:3], v[2:3], v[148:149]
	v_pk_mul_f32 v[0:1], v[0:1], v[146:147]
	v_pk_mul_f32 v[60:61], v[60:61], v[130:131]
	v_pk_mul_f32 v[56:57], v[56:57], v[134:135]
	v_pk_mul_f32 v[52:53], v[52:53], v[138:139]
	v_pk_mul_f32 v[62:63], v[62:63], v[132:133]
	v_pk_mul_f32 v[58:59], v[58:59], v[136:137]
	v_pk_mul_f32 v[54:55], v[54:55], v[140:141]
	v_pk_mul_f32 v[50:51], v[50:51], v[148:149]
	v_pk_mul_f32 v[48:49], v[48:49], v[146:147]
	v_pk_mul_f32 v[44:45], v[44:45], v[130:131]
	v_pk_mul_f32 v[40:41], v[40:41], v[134:135]
	v_pk_mul_f32 v[36:37], v[36:37], v[138:139]
	v_pk_mul_f32 v[46:47], v[46:47], v[132:133]
	v_pk_mul_f32 v[42:43], v[42:43], v[136:137]
	v_pk_mul_f32 v[38:39], v[38:39], v[140:141]
	v_pk_mul_f32 v[34:35], v[34:35], v[148:149]
	v_pk_mul_f32 v[32:33], v[32:33], v[146:147]
	v_pk_mul_f32 v[28:29], v[28:29], v[130:131]
	v_pk_mul_f32 v[24:25], v[24:25], v[134:135]
	v_pk_mul_f32 v[20:21], v[20:21], v[138:139]
	v_pk_mul_f32 v[30:31], v[30:31], v[132:133]
	v_pk_mul_f32 v[26:27], v[26:27], v[136:137]
	v_pk_mul_f32 v[22:23], v[22:23], v[140:141]
	v_pk_mul_f32 v[18:19], v[18:19], v[148:149]
	v_pk_mul_f32 v[16:17], v[16:17], v[146:147]
	s_branch .LBB0_766
